# up-GEMM: the 66 units of the partial 12th round are handed out dynamically (one atomic ticket per workgroup) to the workgroups that finish their 11 static units first
# speedup vs baseline: 1.0172x; 1.0172x over previous
;     __device__ __forceinline__ bool next(int i, Unit& u) const { if (i > 0 || c >= nN) return false; u.pm = pm; u.pn = c; return true; }
;     __host__ __device__ bool next(int i, Unit& u) const {
;         const long L = (long)i * G + c; if (L >= nwg) return false;
;         int wgid = (int)L; { const int q = nwg / NXCD, r = nwg % NXCD, xcd = wgid % NXCD, off = wgid / NXCD; wgid = (xcd < r ? xcd * (q + 1) : r * (q + 1) + (xcd - r) * q) + off; }
;         const int nig = wgm * nN, gid = wgid / nig, fm = gid * wgm, gsz = (nM - fm) < wgm ? (nM - fm) : wgm;
;         u.pm = fm + ((wgid % nig) % gsz); u.pn = (wgid % nig) / gsz; return true;
; template <class Epi, class Sched, bool ALIGN_EPI = false, bool SP2 = false>
; __device__ __forceinline__ void gemm_phase(PG8_LAS unsigned char* lds, const Gemm g, const Sched& S, const Epi& E, int wid0) {
;     ...
;         const bool has_next = S.next(ui + 1, nxt);
.LBB0_547:
	s_add_i32 s84, s59, 1
	s_mul_i32 s2, s84, s50
	s_mul_hi_u32 s3, s84, s38
	s_add_i32 s3, s3, s2
	s_mul_i32 s2, s84, s38
	s_add_u32 s2, s2, s33
	s_addc_u32 s3, s3, s39
	s_cmp_lg_u32 s84, 11
	s_cbranch_scc1 .Ldyn_skip
	v_readlane_b32 s4, v255, 40
	s_cmp_lg_u32 s4, 0
	s_cbranch_scc1 .Ldyn_wait
	v_readlane_b32 s4, v255, 38
	v_readlane_b32 s5, v255, 39
	v_readlane_b32 s2, v255, 41
	s_nop 4
	s_load_dwordx2 s[4:5], s[4:5], 0x98
	s_lshl_b32 s2, s2, 2
	v_mov_b32_e32 v3, s2
	v_mov_b32_e32 v2, 1
	s_mov_b64 s[2:3], exec
	s_mov_b64 exec, 1
	s_waitcnt lgkmcnt(0)
	global_atomic_add v2, v3, v2, s[4:5] sc0
	s_waitcnt vmcnt(0)
	v_add_u32_e32 v2, 0xb00, v2
	v_mov_b32_e32 v3, 0x25f08
	ds_write_b32 v3, v2
	s_waitcnt lgkmcnt(0)
	s_mov_b64 exec, s[2:3]
.Ldyn_wait:
	s_barrier
	v_mov_b32_e32 v3, 0x25f08
	ds_read_b32 v2, v3
	s_waitcnt lgkmcnt(0)
	v_readfirstlane_b32 s2, v2
	s_mov_b32 s3, 0
.Ldyn_skip:
	v_mov_b64_e32 v[2:3], 0xb42
	v_cmp_lt_i64_e64 s[4:5], s[2:3], v[2:3]
	v_mov_b64_e32 v[2:3], 0xb41
	v_cmp_gt_i64_e32 vcc, s[2:3], v[2:3]
	s_cbranch_vccnz .LBB0_553
	s_ashr_i32 s3, s2, 31
	s_lshr_b32 s3, s3, 29
	s_add_i32 s44, s2, s3
	s_and_b32 s3, s44, -8
	s_sub_i32 s45, s2, s3
	s_cmp_gt_i32 s45, 1
	s_mov_b64 s[2:3], -1
	s_cbranch_scc0 .LBB0_550
	s_mul_i32 s2, s45, 0x168
	s_or_b32 s48, s2, 2
	s_mov_b64 s[2:3], 0
